# e7 plus phase-0 adaLN modulation GEMV k-loop rewritten with 32 weight-row loads in flight per wave (was 8), same f32 fma order
# baseline (speedup 1.0000x reference)
.LBB0_249:
	v_mfma_f32_32x32x16_bf16 v[130:145], v[206:209], v[174:177], 0
	s_mov_b32 s40, s15
	s_mov_b32 s0, s35
	s_mov_b32 s1, s14
	v_lshl_add_u32 v211, s34, 1, v251
	ds_read_b64_tr_b16 v[68:69], v211 offset:24576
	ds_read_b64_tr_b16 v[70:71], v211 offset:25088
	v_add_f32_e32 v67, v98, v99
	v_add_f32_e32 v67, v100, v67
	v_add_f32_e32 v67, v101, v67
	v_add_f32_e32 v67, v102, v67
	v_add_f32_e32 v67, v103, v67
	v_cvt_pk_bf16_f32 v158, v98, v99
	v_cvt_pk_bf16_f32 v159, v100, v101
	ds_read_b64_tr_b16 v[72:73], v211 offset:28672
	ds_read_b64_tr_b16 v[74:75], v211 offset:29184
	v_add_f32_e32 v67, v104, v67
	v_add_f32_e32 v67, v105, v67
	v_add_f32_e32 v67, v106, v67
	v_add_f32_e32 v67, v107, v67
	v_cvt_pk_bf16_f32 v160, v102, v103
	v_cvt_pk_bf16_f32 v161, v104, v105
	s_waitcnt lgkmcnt(10)
	v_mfma_f32_32x32x16_bf16 v[114:129], v[198:201], v[174:177], 0
	ds_read_b64_tr_b16 v[76:77], v211 offset:25600
	ds_read_b64_tr_b16 v[78:79], v211 offset:26112
	v_add_f32_e32 v67, v108, v67
	v_add_f32_e32 v67, v109, v67
	v_add_f32_e32 v67, v110, v67
	v_add_f32_e32 v67, v111, v67
	v_cvt_pk_bf16_f32 v154, v106, v107
	v_cvt_pk_bf16_f32 v155, v108, v109
	s_waitcnt lgkmcnt(11)
	v_mfma_f32_32x32x16_bf16 v[130:145], v[202:205], v[170:173], v[130:145]
	ds_read_b64_tr_b16 v[98:99], v211 offset:29696
	ds_read_b64_tr_b16 v[100:101], v211 offset:30208
	v_add_f32_e32 v67, v112, v67
	v_add_f32_e32 v67, v113, v67
	v_add_f32_e32 v67, v82, v67
	v_add_f32_e32 v67, v83, v67
	v_cvt_pk_bf16_f32 v156, v110, v111
	v_cvt_pk_bf16_f32 v157, v112, v113
	s_waitcnt lgkmcnt(12)
	v_mfma_f32_32x32x16_bf16 v[114:129], v[194:197], v[170:173], v[114:129]
	ds_read_b64_tr_b16 v[102:103], v211 offset:26624
	ds_read_b64_tr_b16 v[104:105], v211 offset:27136
	v_add_f32_e32 v67, v84, v67
	v_add_f32_e32 v67, v85, v67
	v_add_f32_e32 v67, v86, v67
	v_add_f32_e32 v67, v87, v67
	v_cvt_pk_bf16_f32 v150, v82, v83
	v_cvt_pk_bf16_f32 v151, v84, v85
	s_waitcnt lgkmcnt(13)
	v_mfma_f32_32x32x16_bf16 v[130:145], v[190:193], v[166:169], v[130:145]
	ds_read_b64_tr_b16 v[106:107], v211 offset:30720
	ds_read_b64_tr_b16 v[108:109], v211 offset:31232
	v_add_f32_e32 v67, v88, v67
	v_add_f32_e32 v67, v89, v67
	v_add_f32_e32 v67, v90, v67
	v_add_f32_e32 v67, v91, v67
	v_cvt_pk_bf16_f32 v152, v86, v87
	v_cvt_pk_bf16_f32 v153, v88, v89
	s_waitcnt lgkmcnt(14)
	v_mfma_f32_32x32x16_bf16 v[114:129], v[186:189], v[166:169], v[114:129]
	ds_read_b64_tr_b16 v[110:111], v211 offset:27648
	ds_read_b64_tr_b16 v[112:113], v211 offset:28160
	v_add_f32_e32 v67, v92, v67
	v_add_f32_e32 v67, v93, v67
	v_add_f32_e32 v67, v94, v67
	v_add_f32_e32 v67, v95, v67
	v_cvt_pk_bf16_f32 v146, v90, v91
	v_cvt_pk_bf16_f32 v147, v92, v93
	s_waitcnt lgkmcnt(14)
	v_mfma_f32_32x32x16_bf16 v[130:145], v[182:185], v[162:165], v[130:145]
	ds_read_b64_tr_b16 v[88:89], v211 offset:31744
	ds_read_b64_tr_b16 v[90:91], v211 offset:32256
	v_add_f32_e32 v67, v96, v67
	v_add_f32_e32 v67, v97, v67
	v_add_f32_e32 v67, 0, v67
	v_cvt_pk_bf16_f32 v148, v94, v95
	v_cvt_pk_bf16_f32 v149, v96, v97
	v_mfma_f32_32x32x16_bf16 v[114:129], v[178:181], v[162:165], v[114:129]
	v_lshl_add_u64 v[190:191], v[226:227], 0, s[2:3]
	s_add_i32 s14, s14, s18
	v_lshl_add_u64 v[80:81], v[190:191], 0, s[70:71]
	s_mov_b32 s15, m0
	s_mov_b32 m0, s14
	s_nop 0
	global_load_lds_dwordx4 v[80:81], off
	s_mov_b32 m0, s15
	v_lshl_add_u64 v[192:193], v[228:229], 0, s[2:3]
	s_lshl_b32 s14, s40, 1
	v_lshl_add_u64 v[80:81], v[192:193], 0, s[58:59]
	s_add_i32 s14, s14, s19
	s_mov_b32 s15, m0
	s_mov_b32 m0, s14
	s_nop 0
	global_load_lds_dwordx4 v[80:81], off
	s_mov_b32 m0, s15
	v_lshl_add_u64 v[194:195], v[230:231], 0, s[2:3]
	v_lshl_add_u64 v[80:81], v[194:195], 0, s[58:59]
	s_addk_i32 s14, 0x2000
	s_mov_b32 s15, m0
	s_mov_b32 m0, s14
	s_nop 0
	global_load_lds_dwordx4 v[80:81], off
	s_mov_b32 m0, s15
	s_waitcnt lgkmcnt(14)
	v_mfma_f32_32x32x16_bf16 v[34:49], v[158:161], v[68:71], v[34:49]
	v_exp_f32_e32 v130, v130
	v_exp_f32_e32 v131, v131
	ds_read_b64_tr_b16 v[92:93], v211 offset:32768
	ds_read_b64_tr_b16 v[94:95], v211 offset:33280
	s_waitcnt lgkmcnt(14)
	v_mfma_f32_32x32x16_bf16 v[50:65], v[158:161], v[72:75], v[50:65]
	v_exp_f32_e32 v132, v132
	v_exp_f32_e32 v133, v133
	ds_read_b64_tr_b16 v[196:197], v211 offset:36864
	ds_read_b64_tr_b16 v[198:199], v211 offset:37376
	v_add_u32_e32 v68, s40, v249
	ds_read_b128 v[84:87], v68
	ds_read_b128 v[80:83], v68 offset:512
	s_waitcnt lgkmcnt(14)
	v_mfma_f32_32x32x16_bf16 v[34:49], v[154:157], v[76:79], v[34:49]
	v_exp_f32_e32 v134, v134
	v_exp_f32_e32 v135, v135
	ds_read_b64_tr_b16 v[200:201], v211 offset:33792
	ds_read_b64_tr_b16 v[202:203], v211 offset:34304
	ds_read_b128 v[186:189], v68 offset:2048
	ds_read_b128 v[182:185], v68 offset:2560
	v_mfma_f32_32x32x16_bf16 v[50:65], v[154:157], v[98:101], v[50:65]
	v_exp_f32_e32 v136, v136
	v_exp_f32_e32 v137, v137
	ds_read_b64_tr_b16 v[96:97], v211 offset:37888
	ds_read_b64_tr_b16 v[98:99], v211 offset:38400
	ds_read_b128 v[178:181], v68 offset:4096
	ds_read_b128 v[76:79], v68 offset:4608
	s_waitcnt lgkmcnt(14)
	v_mfma_f32_32x32x16_bf16 v[34:49], v[150:153], v[102:105], v[34:49]
	v_exp_f32_e32 v138, v138
	v_exp_f32_e32 v139, v139
	ds_read_b64_tr_b16 v[100:101], v211 offset:34816
	ds_read_b64_tr_b16 v[102:103], v211 offset:35328
	ds_read_b128 v[72:75], v68 offset:6144
	ds_read_b128 v[68:71], v68 offset:6656
	v_mfma_f32_32x32x16_bf16 v[50:65], v[150:153], v[106:109], v[50:65]
	v_exp_f32_e32 v140, v140
	v_exp_f32_e32 v141, v141
	ds_read_b64_tr_b16 v[104:105], v211 offset:38912
	ds_read_b64_tr_b16 v[106:107], v211 offset:39424
	v_mfma_f32_32x32x16_bf16 v[34:49], v[146:149], v[110:113], v[34:49]
	v_exp_f32_e32 v142, v142
	v_exp_f32_e32 v143, v143
	ds_read_b64_tr_b16 v[108:109], v211 offset:35840
	ds_read_b64_tr_b16 v[110:111], v211 offset:36352
	v_mfma_f32_32x32x16_bf16 v[50:65], v[146:149], v[88:91], v[50:65]
	v_exp_f32_e32 v144, v144
	v_exp_f32_e32 v145, v145
	ds_read_b64_tr_b16 v[88:89], v211 offset:39936
	ds_read_b64_tr_b16 v[90:91], v211 offset:40448
	s_waitcnt lgkmcnt(14)
	v_mfma_f32_32x32x16_bf16 v[2:17], v[158:161], v[92:95], v[2:17]
	v_exp_f32_e32 v114, v114
	v_exp_f32_e32 v115, v115
	v_mfma_f32_32x32x16_bf16 v[18:33], v[158:161], v[196:199], v[18:33]
	v_exp_f32_e32 v116, v116
	v_exp_f32_e32 v117, v117
	v_mfma_f32_32x32x16_bf16 v[2:17], v[154:157], v[200:203], v[2:17]
	v_exp_f32_e32 v118, v118
	v_exp_f32_e32 v119, v119
	s_waitcnt lgkmcnt(12)
	v_mfma_f32_32x32x16_bf16 v[18:33], v[154:157], v[96:99], v[18:33]
	v_exp_f32_e32 v120, v120
	v_exp_f32_e32 v121, v121
	s_waitcnt lgkmcnt(8)
	v_mfma_f32_32x32x16_bf16 v[2:17], v[150:153], v[100:103], v[2:17]
	v_exp_f32_e32 v122, v122
	v_exp_f32_e32 v123, v123
	s_waitcnt lgkmcnt(4)
	v_mfma_f32_32x32x16_bf16 v[18:33], v[150:153], v[104:107], v[18:33]
	v_exp_f32_e32 v124, v124
	v_exp_f32_e32 v125, v125
	s_waitcnt lgkmcnt(2)
	v_mfma_f32_32x32x16_bf16 v[2:17], v[146:149], v[108:111], v[2:17]
	v_exp_f32_e32 v126, v126
	v_exp_f32_e32 v127, v127
	v_exp_f32_e32 v128, v128
	v_exp_f32_e32 v129, v129
	s_waitcnt lgkmcnt(0)
	v_mfma_f32_32x32x16_bf16 v[18:33], v[146:149], v[88:91], v[18:33]
	s_waitcnt vmcnt(3) lgkmcnt(0)
	s_barrier
	v_mfma_f32_32x32x16_bf16 v[98:113], v[84:87], v[174:177], 0
	s_add_i32 s14, s40, 0x2000
	s_cmpk_lg_i32 s40, 0x4000
	s_cselect_b32 s14, s14, 0
	v_lshl_add_u32 v211, s1, 1, v251
	ds_read_b64_tr_b16 v[196:197], v211 offset:24576
	ds_read_b64_tr_b16 v[198:199], v211 offset:25088
	v_add_f32_e32 v88, v130, v131
	v_add_f32_e32 v88, v132, v88
	v_add_f32_e32 v88, v133, v88
	v_add_f32_e32 v88, v134, v88
	v_add_f32_e32 v88, v135, v88
	v_cvt_pk_bf16_f32 v158, v130, v131
	v_cvt_pk_bf16_f32 v159, v132, v133
	ds_read_b64_tr_b16 v[130:131], v211 offset:28672
	ds_read_b64_tr_b16 v[132:133], v211 offset:29184
	v_add_f32_e32 v84, v136, v88
	v_add_f32_e32 v84, v137, v84
	v_add_f32_e32 v84, v138, v84
	v_add_f32_e32 v146, v139, v84
	v_mfma_f32_32x32x16_bf16 v[82:97], v[80:83], v[174:177], 0
	v_cvt_pk_bf16_f32 v160, v134, v135
	v_cvt_pk_bf16_f32 v161, v136, v137
	ds_read_b64_tr_b16 v[134:135], v211 offset:25600
	ds_read_b64_tr_b16 v[136:137], v211 offset:26112
	v_mfma_f32_32x32x16_bf16 v[98:113], v[186:189], v[170:173], v[98:113]
	v_add_f32_e32 v80, v140, v146
	v_add_f32_e32 v80, v141, v80
	v_add_f32_e32 v80, v142, v80
	v_add_f32_e32 v80, v143, v80
	v_cvt_pk_bf16_f32 v154, v138, v139
	v_cvt_pk_bf16_f32 v155, v140, v141
	ds_read_b64_tr_b16 v[138:139], v211 offset:29696
	ds_read_b64_tr_b16 v[140:141], v211 offset:30208
	v_mfma_f32_32x32x16_bf16 v[82:97], v[182:185], v[170:173], v[82:97]
	v_add_f32_e32 v80, v144, v80
	v_add_f32_e32 v80, v145, v80
	v_add_f32_e32 v80, v114, v80
	v_add_f32_e32 v80, v115, v80
	v_cvt_pk_bf16_f32 v156, v142, v143
	v_cvt_pk_bf16_f32 v157, v144, v145
	ds_read_b64_tr_b16 v[142:143], v211 offset:26624
	ds_read_b64_tr_b16 v[144:145], v211 offset:27136
	v_mfma_f32_32x32x16_bf16 v[98:113], v[178:181], v[166:169], v[98:113]
	v_add_f32_e32 v80, v116, v80
	v_add_f32_e32 v80, v117, v80
	v_add_f32_e32 v80, v118, v80
	v_add_f32_e32 v80, v119, v80
	v_cvt_pk_bf16_f32 v150, v114, v115
	v_cvt_pk_bf16_f32 v151, v116, v117
	ds_read_b64_tr_b16 v[114:115], v211 offset:30720
	ds_read_b64_tr_b16 v[116:117], v211 offset:31232
	v_mfma_f32_32x32x16_bf16 v[82:97], v[76:79], v[166:169], v[82:97]
	v_add_f32_e32 v76, v120, v80
	v_add_f32_e32 v76, v121, v76
	v_add_f32_e32 v76, v122, v76
	v_add_f32_e32 v80, v123, v76
	v_cvt_pk_bf16_f32 v152, v118, v119
	v_cvt_pk_bf16_f32 v153, v120, v121
	ds_read_b64_tr_b16 v[76:77], v211 offset:27648
	ds_read_b64_tr_b16 v[78:79], v211 offset:28160
	v_mfma_f32_32x32x16_bf16 v[98:113], v[72:75], v[162:165], v[98:113]
	v_add_f32_e32 v72, v124, v80
	v_add_f32_e32 v72, v125, v72
	v_add_f32_e32 v72, v126, v72
	v_add_f32_e32 v80, v127, v72
	v_cvt_pk_bf16_f32 v146, v122, v123
	v_cvt_pk_bf16_f32 v147, v124, v125
	ds_read_b64_tr_b16 v[72:73], v211 offset:31744
	ds_read_b64_tr_b16 v[74:75], v211 offset:32256
	v_mfma_f32_32x32x16_bf16 v[82:97], v[68:71], v[162:165], v[82:97]
	v_add_f32_e32 v68, v128, v80
	v_add_f32_e32 v68, v129, v68
	v_add_f32_e32 v80, 0, v68
	v_cvt_pk_bf16_f32 v148, v126, v127
	v_cvt_pk_bf16_f32 v149, v128, v129
	s_add_i32 s1, s40, s18
	v_lshl_add_u64 v[68:69], v[190:191], 0, s[62:63]
	s_mov_b32 s15, m0
	s_mov_b32 m0, s1
	s_nop 0
	global_load_lds_dwordx4 v[68:69], off
	s_mov_b32 m0, s15
	s_lshl_b32 s1, s14, 1
	v_lshl_add_u64 v[68:69], v[192:193], 0, s[60:61]
	s_add_i32 s1, s1, s19
	s_mov_b32 s15, m0
	s_mov_b32 m0, s1
	s_nop 0
	global_load_lds_dwordx4 v[68:69], off
	s_mov_b32 m0, s15
	v_lshl_add_u64 v[68:69], v[194:195], 0, s[60:61]
	s_addk_i32 s1, 0x2000
	s_mov_b32 s15, m0
	s_mov_b32 m0, s1
	s_nop 0
	global_load_lds_dwordx4 v[68:69], off
	s_mov_b32 m0, s15
	s_waitcnt lgkmcnt(14)
	v_mfma_f32_32x32x16_bf16 v[34:49], v[158:161], v[196:199], v[34:49]
	v_exp_f32_e32 v98, v98
	v_exp_f32_e32 v99, v99
	ds_read_b64_tr_b16 v[68:69], v211 offset:32768
	ds_read_b64_tr_b16 v[70:71], v211 offset:33280
	s_waitcnt lgkmcnt(14)
	v_mfma_f32_32x32x16_bf16 v[50:65], v[158:161], v[130:133], v[50:65]
	v_exp_f32_e32 v100, v100
	v_exp_f32_e32 v101, v101
	ds_read_b64_tr_b16 v[118:119], v211 offset:36864
	ds_read_b64_tr_b16 v[120:121], v211 offset:37376
	v_add_u32_e32 v81, s14, v249
	ds_read_b128 v[206:209], v81
	ds_read_b128 v[198:201], v81 offset:512
	s_waitcnt lgkmcnt(14)
	v_mfma_f32_32x32x16_bf16 v[34:49], v[154:157], v[134:137], v[34:49]
	v_exp_f32_e32 v102, v102
	v_exp_f32_e32 v103, v103
	ds_read_b64_tr_b16 v[122:123], v211 offset:33792
	ds_read_b64_tr_b16 v[124:125], v211 offset:34304
	ds_read_b128 v[202:205], v81 offset:2048
	ds_read_b128 v[194:197], v81 offset:2560
	v_mfma_f32_32x32x16_bf16 v[50:65], v[154:157], v[138:141], v[50:65]
	v_exp_f32_e32 v104, v104
	v_exp_f32_e32 v105, v105
	ds_read_b64_tr_b16 v[126:127], v211 offset:37888
	ds_read_b64_tr_b16 v[128:129], v211 offset:38400
	ds_read_b128 v[190:193], v81 offset:4096
	ds_read_b128 v[186:189], v81 offset:4608
	s_waitcnt lgkmcnt(14)
	v_mfma_f32_32x32x16_bf16 v[34:49], v[150:153], v[142:145], v[34:49]
	v_exp_f32_e32 v106, v106
	v_exp_f32_e32 v107, v107
	ds_read_b64_tr_b16 v[130:131], v211 offset:34816
	ds_read_b64_tr_b16 v[132:133], v211 offset:35328
	ds_read_b128 v[182:185], v81 offset:6144
	ds_read_b128 v[178:181], v81 offset:6656
	v_mfma_f32_32x32x16_bf16 v[50:65], v[150:153], v[114:117], v[50:65]
	v_exp_f32_e32 v108, v108
	v_exp_f32_e32 v109, v109
	ds_read_b64_tr_b16 v[114:115], v211 offset:38912
	ds_read_b64_tr_b16 v[116:117], v211 offset:39424
	v_mfma_f32_32x32x16_bf16 v[34:49], v[146:149], v[76:79], v[34:49]
	v_exp_f32_e32 v110, v110
	v_exp_f32_e32 v111, v111
	ds_read_b64_tr_b16 v[76:77], v211 offset:35840
	ds_read_b64_tr_b16 v[78:79], v211 offset:36352
	v_mfma_f32_32x32x16_bf16 v[50:65], v[146:149], v[72:75], v[50:65]
	v_exp_f32_e32 v112, v112
	v_exp_f32_e32 v113, v113
	ds_read_b64_tr_b16 v[72:73], v211 offset:39936
	ds_read_b64_tr_b16 v[74:75], v211 offset:40448
	s_waitcnt lgkmcnt(14)
	v_mfma_f32_32x32x16_bf16 v[2:17], v[158:161], v[68:71], v[2:17]
	v_exp_f32_e32 v82, v82
	v_exp_f32_e32 v83, v83
	v_mfma_f32_32x32x16_bf16 v[18:33], v[158:161], v[118:121], v[18:33]
	v_exp_f32_e32 v84, v84
	v_exp_f32_e32 v85, v85
	v_mfma_f32_32x32x16_bf16 v[2:17], v[154:157], v[122:125], v[2:17]
	v_exp_f32_e32 v86, v86
	v_exp_f32_e32 v87, v87
	s_waitcnt lgkmcnt(12)
	v_mfma_f32_32x32x16_bf16 v[18:33], v[154:157], v[126:129], v[18:33]
	v_exp_f32_e32 v88, v88
	v_exp_f32_e32 v89, v89
	s_waitcnt lgkmcnt(8)
	v_mfma_f32_32x32x16_bf16 v[2:17], v[150:153], v[130:133], v[2:17]
	v_exp_f32_e32 v90, v90
	v_exp_f32_e32 v91, v91
	s_waitcnt lgkmcnt(4)
	v_mfma_f32_32x32x16_bf16 v[18:33], v[150:153], v[114:117], v[18:33]
	v_exp_f32_e32 v92, v92
	v_exp_f32_e32 v93, v93
	s_waitcnt lgkmcnt(2)
	v_mfma_f32_32x32x16_bf16 v[2:17], v[146:149], v[76:79], v[2:17]
	v_exp_f32_e32 v94, v94
	v_exp_f32_e32 v95, v95
	v_exp_f32_e32 v96, v96
	v_exp_f32_e32 v97, v97
	s_add_i32 s1, s14, 0x2000
	s_cmpk_lg_i32 s14, 0x4000
	s_cselect_b32 s15, s1, 0
	s_add_i32 s35, s35, 2
	s_add_u32 s2, s2, 0x40000
	v_add_f32_e32 v66, v66, v67
	s_addc_u32 s3, s3, 0
	s_mov_b32 s34, s40
	v_add_f32_e32 v66, v66, v80
	s_cmp_ge_u32 s35, s29
	s_waitcnt lgkmcnt(0)
	v_mfma_f32_32x32x16_bf16 v[18:33], v[146:149], v[72:75], v[18:33]
	s_waitcnt vmcnt(3) lgkmcnt(0)
	s_barrier
	s_cbranch_scc0 .LBB0_249
	s_add_i32 s50, s0, -5
	s_lshl_b64 s[86:87], s[4:5], 10
	s_add_i32 s0, s50, 1
	s_cmp_lt_u32 s0, s29
	s_cbranch_scc0 .LBB0_254

.LBB0_729:
	global_load_dwordx4 v[74:77], v[44:45], off
	v_lshl_add_u64 v[2:3], v[44:45], 0, s[26:27]
	global_load_dwordx4 v[78:81], v[2:3], off
	v_lshl_add_u64 v[2:3], v[2:3], 0, s[26:27]
	global_load_dwordx4 v[82:85], v[2:3], off
	v_lshl_add_u64 v[2:3], v[2:3], 0, s[26:27]
	global_load_dwordx4 v[86:89], v[2:3], off
	v_lshl_add_u64 v[2:3], v[2:3], 0, s[26:27]
	global_load_dwordx4 v[90:93], v[2:3], off
	v_lshl_add_u64 v[2:3], v[2:3], 0, s[26:27]
	global_load_dwordx4 v[94:97], v[2:3], off
	v_lshl_add_u64 v[2:3], v[2:3], 0, s[26:27]
	global_load_dwordx4 v[98:101], v[2:3], off
	v_lshl_add_u64 v[2:3], v[2:3], 0, s[26:27]
	global_load_dwordx4 v[102:105], v[2:3], off
	v_lshl_add_u64 v[2:3], v[2:3], 0, s[26:27]
	global_load_dwordx4 v[106:109], v[2:3], off
	v_lshl_add_u64 v[2:3], v[2:3], 0, s[26:27]
	global_load_dwordx4 v[110:113], v[2:3], off
	v_lshl_add_u64 v[2:3], v[2:3], 0, s[26:27]
	global_load_dwordx4 v[114:117], v[2:3], off
	v_lshl_add_u64 v[2:3], v[2:3], 0, s[26:27]
	global_load_dwordx4 v[118:121], v[2:3], off
	v_lshl_add_u64 v[2:3], v[2:3], 0, s[26:27]
	global_load_dwordx4 v[122:125], v[2:3], off
	v_lshl_add_u64 v[2:3], v[2:3], 0, s[26:27]
	global_load_dwordx4 v[126:129], v[2:3], off
	v_lshl_add_u64 v[2:3], v[2:3], 0, s[26:27]
	global_load_dwordx4 v[130:133], v[2:3], off
	v_lshl_add_u64 v[2:3], v[2:3], 0, s[26:27]
	global_load_dwordx4 v[134:137], v[2:3], off
	v_lshl_add_u64 v[2:3], v[2:3], 0, s[26:27]
	global_load_dwordx4 v[138:141], v[2:3], off
	v_lshl_add_u64 v[2:3], v[2:3], 0, s[26:27]
	global_load_dwordx4 v[142:145], v[2:3], off
	v_lshl_add_u64 v[2:3], v[2:3], 0, s[26:27]
	global_load_dwordx4 v[146:149], v[2:3], off
	v_lshl_add_u64 v[2:3], v[2:3], 0, s[26:27]
	global_load_dwordx4 v[150:153], v[2:3], off
	v_lshl_add_u64 v[2:3], v[2:3], 0, s[26:27]
	global_load_dwordx4 v[154:157], v[2:3], off
	v_lshl_add_u64 v[2:3], v[2:3], 0, s[26:27]
	global_load_dwordx4 v[158:161], v[2:3], off
	v_lshl_add_u64 v[2:3], v[2:3], 0, s[26:27]
	global_load_dwordx4 v[162:165], v[2:3], off
	v_lshl_add_u64 v[2:3], v[2:3], 0, s[26:27]
	global_load_dwordx4 v[166:169], v[2:3], off
	v_lshl_add_u64 v[2:3], v[2:3], 0, s[26:27]
	global_load_dwordx4 v[170:173], v[2:3], off
	v_lshl_add_u64 v[2:3], v[2:3], 0, s[26:27]
	global_load_dwordx4 v[174:177], v[2:3], off
	v_lshl_add_u64 v[2:3], v[2:3], 0, s[26:27]
	global_load_dwordx4 v[178:181], v[2:3], off
	v_lshl_add_u64 v[2:3], v[2:3], 0, s[26:27]
	global_load_dwordx4 v[182:185], v[2:3], off
	v_lshl_add_u64 v[2:3], v[2:3], 0, s[26:27]
	global_load_dwordx4 v[186:189], v[2:3], off
	v_lshl_add_u64 v[2:3], v[2:3], 0, s[26:27]
	global_load_dwordx4 v[190:193], v[2:3], off
	v_lshl_add_u64 v[2:3], v[2:3], 0, s[26:27]
	global_load_dwordx4 v[194:197], v[2:3], off
	v_lshl_add_u64 v[2:3], v[2:3], 0, s[26:27]
	global_load_dwordx4 v[198:201], v[2:3], off
	v_lshl_add_u64 v[44:45], v[2:3], 0, s[26:27]
	v_add_u32_e32 v43, s19, v0
	ds_read_b128 v[202:205], v43
	ds_read_b128 v[206:209], v43 offset:16
	ds_read_b128 v[210:213], v43 offset:32
	ds_read_b128 v[214:217], v43 offset:48
	ds_read_b128 v[218:221], v43 offset:64
	ds_read_b128 v[222:225], v43 offset:80
	ds_read_b128 v[226:229], v43 offset:96
	ds_read_b128 v[230:233], v43 offset:112
	s_waitcnt vmcnt(31) lgkmcnt(7)
	v_pk_fma_f32 v[40:41], v[76:77], v[202:203], v[40:41] op_sel_hi:[1,0,1]
	v_pk_fma_f32 v[38:39], v[74:75], v[202:203], v[38:39] op_sel_hi:[1,0,1]
	v_pk_fma_f32 v[36:37], v[76:77], v[202:203], v[36:37] op_sel:[0,1,0]
	v_pk_fma_f32 v[34:35], v[74:75], v[202:203], v[34:35] op_sel:[0,1,0]
	v_pk_fma_f32 v[28:29], v[76:77], v[204:205], v[28:29] op_sel_hi:[1,0,1]
	v_pk_fma_f32 v[26:27], v[74:75], v[204:205], v[26:27] op_sel_hi:[1,0,1]
	v_pk_fma_f32 v[24:25], v[76:77], v[204:205], v[24:25] op_sel:[0,1,0]
	v_pk_fma_f32 v[22:23], v[74:75], v[204:205], v[22:23] op_sel:[0,1,0]
	s_waitcnt vmcnt(30) lgkmcnt(6)
	v_pk_fma_f32 v[40:41], v[80:81], v[206:207], v[40:41] op_sel_hi:[1,0,1]
	v_pk_fma_f32 v[38:39], v[78:79], v[206:207], v[38:39] op_sel_hi:[1,0,1]
	v_pk_fma_f32 v[36:37], v[80:81], v[206:207], v[36:37] op_sel:[0,1,0]
	v_pk_fma_f32 v[34:35], v[78:79], v[206:207], v[34:35] op_sel:[0,1,0]
	v_pk_fma_f32 v[28:29], v[80:81], v[208:209], v[28:29] op_sel_hi:[1,0,1]
	v_pk_fma_f32 v[26:27], v[78:79], v[208:209], v[26:27] op_sel_hi:[1,0,1]
	v_pk_fma_f32 v[24:25], v[80:81], v[208:209], v[24:25] op_sel:[0,1,0]
	v_pk_fma_f32 v[22:23], v[78:79], v[208:209], v[22:23] op_sel:[0,1,0]
	s_waitcnt vmcnt(29) lgkmcnt(5)
	v_pk_fma_f32 v[40:41], v[84:85], v[210:211], v[40:41] op_sel_hi:[1,0,1]
	v_pk_fma_f32 v[38:39], v[82:83], v[210:211], v[38:39] op_sel_hi:[1,0,1]
	v_pk_fma_f32 v[36:37], v[84:85], v[210:211], v[36:37] op_sel:[0,1,0]
	v_pk_fma_f32 v[34:35], v[82:83], v[210:211], v[34:35] op_sel:[0,1,0]
	v_pk_fma_f32 v[28:29], v[84:85], v[212:213], v[28:29] op_sel_hi:[1,0,1]
	v_pk_fma_f32 v[26:27], v[82:83], v[212:213], v[26:27] op_sel_hi:[1,0,1]
	v_pk_fma_f32 v[24:25], v[84:85], v[212:213], v[24:25] op_sel:[0,1,0]
	v_pk_fma_f32 v[22:23], v[82:83], v[212:213], v[22:23] op_sel:[0,1,0]
	s_waitcnt vmcnt(28) lgkmcnt(4)
	v_pk_fma_f32 v[40:41], v[88:89], v[214:215], v[40:41] op_sel_hi:[1,0,1]
	v_pk_fma_f32 v[38:39], v[86:87], v[214:215], v[38:39] op_sel_hi:[1,0,1]
	v_pk_fma_f32 v[36:37], v[88:89], v[214:215], v[36:37] op_sel:[0,1,0]
	v_pk_fma_f32 v[34:35], v[86:87], v[214:215], v[34:35] op_sel:[0,1,0]
	v_pk_fma_f32 v[28:29], v[88:89], v[216:217], v[28:29] op_sel_hi:[1,0,1]
	v_pk_fma_f32 v[26:27], v[86:87], v[216:217], v[26:27] op_sel_hi:[1,0,1]
	v_pk_fma_f32 v[24:25], v[88:89], v[216:217], v[24:25] op_sel:[0,1,0]
	v_pk_fma_f32 v[22:23], v[86:87], v[216:217], v[22:23] op_sel:[0,1,0]
	s_waitcnt vmcnt(27) lgkmcnt(3)
	v_pk_fma_f32 v[40:41], v[92:93], v[218:219], v[40:41] op_sel_hi:[1,0,1]
	v_pk_fma_f32 v[38:39], v[90:91], v[218:219], v[38:39] op_sel_hi:[1,0,1]
	v_pk_fma_f32 v[36:37], v[92:93], v[218:219], v[36:37] op_sel:[0,1,0]
	v_pk_fma_f32 v[34:35], v[90:91], v[218:219], v[34:35] op_sel:[0,1,0]
	v_pk_fma_f32 v[28:29], v[92:93], v[220:221], v[28:29] op_sel_hi:[1,0,1]
	v_pk_fma_f32 v[26:27], v[90:91], v[220:221], v[26:27] op_sel_hi:[1,0,1]
	v_pk_fma_f32 v[24:25], v[92:93], v[220:221], v[24:25] op_sel:[0,1,0]
	v_pk_fma_f32 v[22:23], v[90:91], v[220:221], v[22:23] op_sel:[0,1,0]
	s_waitcnt vmcnt(26) lgkmcnt(2)
	v_pk_fma_f32 v[40:41], v[96:97], v[222:223], v[40:41] op_sel_hi:[1,0,1]
	v_pk_fma_f32 v[38:39], v[94:95], v[222:223], v[38:39] op_sel_hi:[1,0,1]
	v_pk_fma_f32 v[36:37], v[96:97], v[222:223], v[36:37] op_sel:[0,1,0]
	v_pk_fma_f32 v[34:35], v[94:95], v[222:223], v[34:35] op_sel:[0,1,0]
	v_pk_fma_f32 v[28:29], v[96:97], v[224:225], v[28:29] op_sel_hi:[1,0,1]
	v_pk_fma_f32 v[26:27], v[94:95], v[224:225], v[26:27] op_sel_hi:[1,0,1]
	v_pk_fma_f32 v[24:25], v[96:97], v[224:225], v[24:25] op_sel:[0,1,0]
	v_pk_fma_f32 v[22:23], v[94:95], v[224:225], v[22:23] op_sel:[0,1,0]
	s_waitcnt vmcnt(25) lgkmcnt(1)
	v_pk_fma_f32 v[40:41], v[100:101], v[226:227], v[40:41] op_sel_hi:[1,0,1]
	v_pk_fma_f32 v[38:39], v[98:99], v[226:227], v[38:39] op_sel_hi:[1,0,1]
	v_pk_fma_f32 v[36:37], v[100:101], v[226:227], v[36:37] op_sel:[0,1,0]
	v_pk_fma_f32 v[34:35], v[98:99], v[226:227], v[34:35] op_sel:[0,1,0]
	v_pk_fma_f32 v[28:29], v[100:101], v[228:229], v[28:29] op_sel_hi:[1,0,1]
	v_pk_fma_f32 v[26:27], v[98:99], v[228:229], v[26:27] op_sel_hi:[1,0,1]
	v_pk_fma_f32 v[24:25], v[100:101], v[228:229], v[24:25] op_sel:[0,1,0]
	v_pk_fma_f32 v[22:23], v[98:99], v[228:229], v[22:23] op_sel:[0,1,0]
	s_waitcnt vmcnt(24) lgkmcnt(0)
	v_pk_fma_f32 v[40:41], v[104:105], v[230:231], v[40:41] op_sel_hi:[1,0,1]
	v_pk_fma_f32 v[38:39], v[102:103], v[230:231], v[38:39] op_sel_hi:[1,0,1]
	v_pk_fma_f32 v[36:37], v[104:105], v[230:231], v[36:37] op_sel:[0,1,0]
	v_pk_fma_f32 v[34:35], v[102:103], v[230:231], v[34:35] op_sel:[0,1,0]
	v_pk_fma_f32 v[28:29], v[104:105], v[232:233], v[28:29] op_sel_hi:[1,0,1]
	v_pk_fma_f32 v[26:27], v[102:103], v[232:233], v[26:27] op_sel_hi:[1,0,1]
	v_pk_fma_f32 v[24:25], v[104:105], v[232:233], v[24:25] op_sel:[0,1,0]
	v_pk_fma_f32 v[22:23], v[102:103], v[232:233], v[22:23] op_sel:[0,1,0]
	ds_read_b128 v[202:205], v43 offset:128
	ds_read_b128 v[206:209], v43 offset:144
	ds_read_b128 v[210:213], v43 offset:160
	ds_read_b128 v[214:217], v43 offset:176
	ds_read_b128 v[218:221], v43 offset:192
	ds_read_b128 v[222:225], v43 offset:208
	ds_read_b128 v[226:229], v43 offset:224
	ds_read_b128 v[230:233], v43 offset:240
	s_waitcnt vmcnt(23) lgkmcnt(7)
	v_pk_fma_f32 v[40:41], v[108:109], v[202:203], v[40:41] op_sel_hi:[1,0,1]
	v_pk_fma_f32 v[38:39], v[106:107], v[202:203], v[38:39] op_sel_hi:[1,0,1]
	v_pk_fma_f32 v[36:37], v[108:109], v[202:203], v[36:37] op_sel:[0,1,0]
	v_pk_fma_f32 v[34:35], v[106:107], v[202:203], v[34:35] op_sel:[0,1,0]
	v_pk_fma_f32 v[28:29], v[108:109], v[204:205], v[28:29] op_sel_hi:[1,0,1]
	v_pk_fma_f32 v[26:27], v[106:107], v[204:205], v[26:27] op_sel_hi:[1,0,1]
	v_pk_fma_f32 v[24:25], v[108:109], v[204:205], v[24:25] op_sel:[0,1,0]
	v_pk_fma_f32 v[22:23], v[106:107], v[204:205], v[22:23] op_sel:[0,1,0]
	s_waitcnt vmcnt(22) lgkmcnt(6)
	v_pk_fma_f32 v[40:41], v[112:113], v[206:207], v[40:41] op_sel_hi:[1,0,1]
	v_pk_fma_f32 v[38:39], v[110:111], v[206:207], v[38:39] op_sel_hi:[1,0,1]
	v_pk_fma_f32 v[36:37], v[112:113], v[206:207], v[36:37] op_sel:[0,1,0]
	v_pk_fma_f32 v[34:35], v[110:111], v[206:207], v[34:35] op_sel:[0,1,0]
	v_pk_fma_f32 v[28:29], v[112:113], v[208:209], v[28:29] op_sel_hi:[1,0,1]
	v_pk_fma_f32 v[26:27], v[110:111], v[208:209], v[26:27] op_sel_hi:[1,0,1]
	v_pk_fma_f32 v[24:25], v[112:113], v[208:209], v[24:25] op_sel:[0,1,0]
	v_pk_fma_f32 v[22:23], v[110:111], v[208:209], v[22:23] op_sel:[0,1,0]
	s_waitcnt vmcnt(21) lgkmcnt(5)
	v_pk_fma_f32 v[40:41], v[116:117], v[210:211], v[40:41] op_sel_hi:[1,0,1]
	v_pk_fma_f32 v[38:39], v[114:115], v[210:211], v[38:39] op_sel_hi:[1,0,1]
	v_pk_fma_f32 v[36:37], v[116:117], v[210:211], v[36:37] op_sel:[0,1,0]
	v_pk_fma_f32 v[34:35], v[114:115], v[210:211], v[34:35] op_sel:[0,1,0]
	v_pk_fma_f32 v[28:29], v[116:117], v[212:213], v[28:29] op_sel_hi:[1,0,1]
	v_pk_fma_f32 v[26:27], v[114:115], v[212:213], v[26:27] op_sel_hi:[1,0,1]
	v_pk_fma_f32 v[24:25], v[116:117], v[212:213], v[24:25] op_sel:[0,1,0]
	v_pk_fma_f32 v[22:23], v[114:115], v[212:213], v[22:23] op_sel:[0,1,0]
	s_waitcnt vmcnt(20) lgkmcnt(4)
	v_pk_fma_f32 v[40:41], v[120:121], v[214:215], v[40:41] op_sel_hi:[1,0,1]
	v_pk_fma_f32 v[38:39], v[118:119], v[214:215], v[38:39] op_sel_hi:[1,0,1]
	v_pk_fma_f32 v[36:37], v[120:121], v[214:215], v[36:37] op_sel:[0,1,0]
	v_pk_fma_f32 v[34:35], v[118:119], v[214:215], v[34:35] op_sel:[0,1,0]
	v_pk_fma_f32 v[28:29], v[120:121], v[216:217], v[28:29] op_sel_hi:[1,0,1]
	v_pk_fma_f32 v[26:27], v[118:119], v[216:217], v[26:27] op_sel_hi:[1,0,1]
	v_pk_fma_f32 v[24:25], v[120:121], v[216:217], v[24:25] op_sel:[0,1,0]
	v_pk_fma_f32 v[22:23], v[118:119], v[216:217], v[22:23] op_sel:[0,1,0]
	s_waitcnt vmcnt(19) lgkmcnt(3)
	v_pk_fma_f32 v[40:41], v[124:125], v[218:219], v[40:41] op_sel_hi:[1,0,1]
	v_pk_fma_f32 v[38:39], v[122:123], v[218:219], v[38:39] op_sel_hi:[1,0,1]
	v_pk_fma_f32 v[36:37], v[124:125], v[218:219], v[36:37] op_sel:[0,1,0]
	v_pk_fma_f32 v[34:35], v[122:123], v[218:219], v[34:35] op_sel:[0,1,0]
	v_pk_fma_f32 v[28:29], v[124:125], v[220:221], v[28:29] op_sel_hi:[1,0,1]
	v_pk_fma_f32 v[26:27], v[122:123], v[220:221], v[26:27] op_sel_hi:[1,0,1]
	v_pk_fma_f32 v[24:25], v[124:125], v[220:221], v[24:25] op_sel:[0,1,0]
	v_pk_fma_f32 v[22:23], v[122:123], v[220:221], v[22:23] op_sel:[0,1,0]
	s_waitcnt vmcnt(18) lgkmcnt(2)
	v_pk_fma_f32 v[40:41], v[128:129], v[222:223], v[40:41] op_sel_hi:[1,0,1]
	v_pk_fma_f32 v[38:39], v[126:127], v[222:223], v[38:39] op_sel_hi:[1,0,1]
	v_pk_fma_f32 v[36:37], v[128:129], v[222:223], v[36:37] op_sel:[0,1,0]
	v_pk_fma_f32 v[34:35], v[126:127], v[222:223], v[34:35] op_sel:[0,1,0]
	v_pk_fma_f32 v[28:29], v[128:129], v[224:225], v[28:29] op_sel_hi:[1,0,1]
	v_pk_fma_f32 v[26:27], v[126:127], v[224:225], v[26:27] op_sel_hi:[1,0,1]
	v_pk_fma_f32 v[24:25], v[128:129], v[224:225], v[24:25] op_sel:[0,1,0]
	v_pk_fma_f32 v[22:23], v[126:127], v[224:225], v[22:23] op_sel:[0,1,0]
	s_waitcnt vmcnt(17) lgkmcnt(1)
	v_pk_fma_f32 v[40:41], v[132:133], v[226:227], v[40:41] op_sel_hi:[1,0,1]
	v_pk_fma_f32 v[38:39], v[130:131], v[226:227], v[38:39] op_sel_hi:[1,0,1]
	v_pk_fma_f32 v[36:37], v[132:133], v[226:227], v[36:37] op_sel:[0,1,0]
	v_pk_fma_f32 v[34:35], v[130:131], v[226:227], v[34:35] op_sel:[0,1,0]
	v_pk_fma_f32 v[28:29], v[132:133], v[228:229], v[28:29] op_sel_hi:[1,0,1]
	v_pk_fma_f32 v[26:27], v[130:131], v[228:229], v[26:27] op_sel_hi:[1,0,1]
	v_pk_fma_f32 v[24:25], v[132:133], v[228:229], v[24:25] op_sel:[0,1,0]
	v_pk_fma_f32 v[22:23], v[130:131], v[228:229], v[22:23] op_sel:[0,1,0]
	s_waitcnt vmcnt(16) lgkmcnt(0)
	v_pk_fma_f32 v[40:41], v[136:137], v[230:231], v[40:41] op_sel_hi:[1,0,1]
	v_pk_fma_f32 v[38:39], v[134:135], v[230:231], v[38:39] op_sel_hi:[1,0,1]
	v_pk_fma_f32 v[36:37], v[136:137], v[230:231], v[36:37] op_sel:[0,1,0]
	v_pk_fma_f32 v[34:35], v[134:135], v[230:231], v[34:35] op_sel:[0,1,0]
	v_pk_fma_f32 v[28:29], v[136:137], v[232:233], v[28:29] op_sel_hi:[1,0,1]
	v_pk_fma_f32 v[26:27], v[134:135], v[232:233], v[26:27] op_sel_hi:[1,0,1]
	v_pk_fma_f32 v[24:25], v[136:137], v[232:233], v[24:25] op_sel:[0,1,0]
	v_pk_fma_f32 v[22:23], v[134:135], v[232:233], v[22:23] op_sel:[0,1,0]
	ds_read_b128 v[202:205], v43 offset:256
	ds_read_b128 v[206:209], v43 offset:272
	ds_read_b128 v[210:213], v43 offset:288
	ds_read_b128 v[214:217], v43 offset:304
	ds_read_b128 v[218:221], v43 offset:320
	ds_read_b128 v[222:225], v43 offset:336
	ds_read_b128 v[226:229], v43 offset:352
	ds_read_b128 v[230:233], v43 offset:368
	s_waitcnt vmcnt(15) lgkmcnt(7)
	v_pk_fma_f32 v[40:41], v[140:141], v[202:203], v[40:41] op_sel_hi:[1,0,1]
	v_pk_fma_f32 v[38:39], v[138:139], v[202:203], v[38:39] op_sel_hi:[1,0,1]
	v_pk_fma_f32 v[36:37], v[140:141], v[202:203], v[36:37] op_sel:[0,1,0]
	v_pk_fma_f32 v[34:35], v[138:139], v[202:203], v[34:35] op_sel:[0,1,0]
	v_pk_fma_f32 v[28:29], v[140:141], v[204:205], v[28:29] op_sel_hi:[1,0,1]
	v_pk_fma_f32 v[26:27], v[138:139], v[204:205], v[26:27] op_sel_hi:[1,0,1]
	v_pk_fma_f32 v[24:25], v[140:141], v[204:205], v[24:25] op_sel:[0,1,0]
	v_pk_fma_f32 v[22:23], v[138:139], v[204:205], v[22:23] op_sel:[0,1,0]
	s_waitcnt vmcnt(14) lgkmcnt(6)
	v_pk_fma_f32 v[40:41], v[144:145], v[206:207], v[40:41] op_sel_hi:[1,0,1]
	v_pk_fma_f32 v[38:39], v[142:143], v[206:207], v[38:39] op_sel_hi:[1,0,1]
	v_pk_fma_f32 v[36:37], v[144:145], v[206:207], v[36:37] op_sel:[0,1,0]
	v_pk_fma_f32 v[34:35], v[142:143], v[206:207], v[34:35] op_sel:[0,1,0]
	v_pk_fma_f32 v[28:29], v[144:145], v[208:209], v[28:29] op_sel_hi:[1,0,1]
	v_pk_fma_f32 v[26:27], v[142:143], v[208:209], v[26:27] op_sel_hi:[1,0,1]
	v_pk_fma_f32 v[24:25], v[144:145], v[208:209], v[24:25] op_sel:[0,1,0]
	v_pk_fma_f32 v[22:23], v[142:143], v[208:209], v[22:23] op_sel:[0,1,0]
	s_waitcnt vmcnt(13) lgkmcnt(5)
	v_pk_fma_f32 v[40:41], v[148:149], v[210:211], v[40:41] op_sel_hi:[1,0,1]
	v_pk_fma_f32 v[38:39], v[146:147], v[210:211], v[38:39] op_sel_hi:[1,0,1]
	v_pk_fma_f32 v[36:37], v[148:149], v[210:211], v[36:37] op_sel:[0,1,0]
	v_pk_fma_f32 v[34:35], v[146:147], v[210:211], v[34:35] op_sel:[0,1,0]
	v_pk_fma_f32 v[28:29], v[148:149], v[212:213], v[28:29] op_sel_hi:[1,0,1]
	v_pk_fma_f32 v[26:27], v[146:147], v[212:213], v[26:27] op_sel_hi:[1,0,1]
	v_pk_fma_f32 v[24:25], v[148:149], v[212:213], v[24:25] op_sel:[0,1,0]
	v_pk_fma_f32 v[22:23], v[146:147], v[212:213], v[22:23] op_sel:[0,1,0]
	s_waitcnt vmcnt(12) lgkmcnt(4)
	v_pk_fma_f32 v[40:41], v[152:153], v[214:215], v[40:41] op_sel_hi:[1,0,1]
	v_pk_fma_f32 v[38:39], v[150:151], v[214:215], v[38:39] op_sel_hi:[1,0,1]
	v_pk_fma_f32 v[36:37], v[152:153], v[214:215], v[36:37] op_sel:[0,1,0]
	v_pk_fma_f32 v[34:35], v[150:151], v[214:215], v[34:35] op_sel:[0,1,0]
	v_pk_fma_f32 v[28:29], v[152:153], v[216:217], v[28:29] op_sel_hi:[1,0,1]
	v_pk_fma_f32 v[26:27], v[150:151], v[216:217], v[26:27] op_sel_hi:[1,0,1]
	v_pk_fma_f32 v[24:25], v[152:153], v[216:217], v[24:25] op_sel:[0,1,0]
	v_pk_fma_f32 v[22:23], v[150:151], v[216:217], v[22:23] op_sel:[0,1,0]
	s_waitcnt vmcnt(11) lgkmcnt(3)
	v_pk_fma_f32 v[40:41], v[156:157], v[218:219], v[40:41] op_sel_hi:[1,0,1]
	v_pk_fma_f32 v[38:39], v[154:155], v[218:219], v[38:39] op_sel_hi:[1,0,1]
	v_pk_fma_f32 v[36:37], v[156:157], v[218:219], v[36:37] op_sel:[0,1,0]
	v_pk_fma_f32 v[34:35], v[154:155], v[218:219], v[34:35] op_sel:[0,1,0]
	v_pk_fma_f32 v[28:29], v[156:157], v[220:221], v[28:29] op_sel_hi:[1,0,1]
	v_pk_fma_f32 v[26:27], v[154:155], v[220:221], v[26:27] op_sel_hi:[1,0,1]
	v_pk_fma_f32 v[24:25], v[156:157], v[220:221], v[24:25] op_sel:[0,1,0]
	v_pk_fma_f32 v[22:23], v[154:155], v[220:221], v[22:23] op_sel:[0,1,0]
	s_waitcnt vmcnt(10) lgkmcnt(2)
	v_pk_fma_f32 v[40:41], v[160:161], v[222:223], v[40:41] op_sel_hi:[1,0,1]
	v_pk_fma_f32 v[38:39], v[158:159], v[222:223], v[38:39] op_sel_hi:[1,0,1]
	v_pk_fma_f32 v[36:37], v[160:161], v[222:223], v[36:37] op_sel:[0,1,0]
	v_pk_fma_f32 v[34:35], v[158:159], v[222:223], v[34:35] op_sel:[0,1,0]
	v_pk_fma_f32 v[28:29], v[160:161], v[224:225], v[28:29] op_sel_hi:[1,0,1]
	v_pk_fma_f32 v[26:27], v[158:159], v[224:225], v[26:27] op_sel_hi:[1,0,1]
	v_pk_fma_f32 v[24:25], v[160:161], v[224:225], v[24:25] op_sel:[0,1,0]
	v_pk_fma_f32 v[22:23], v[158:159], v[224:225], v[22:23] op_sel:[0,1,0]
	s_waitcnt vmcnt(9) lgkmcnt(1)
	v_pk_fma_f32 v[40:41], v[164:165], v[226:227], v[40:41] op_sel_hi:[1,0,1]
	v_pk_fma_f32 v[38:39], v[162:163], v[226:227], v[38:39] op_sel_hi:[1,0,1]
	v_pk_fma_f32 v[36:37], v[164:165], v[226:227], v[36:37] op_sel:[0,1,0]
	v_pk_fma_f32 v[34:35], v[162:163], v[226:227], v[34:35] op_sel:[0,1,0]
	v_pk_fma_f32 v[28:29], v[164:165], v[228:229], v[28:29] op_sel_hi:[1,0,1]
	v_pk_fma_f32 v[26:27], v[162:163], v[228:229], v[26:27] op_sel_hi:[1,0,1]
	v_pk_fma_f32 v[24:25], v[164:165], v[228:229], v[24:25] op_sel:[0,1,0]
	v_pk_fma_f32 v[22:23], v[162:163], v[228:229], v[22:23] op_sel:[0,1,0]
	s_waitcnt vmcnt(8) lgkmcnt(0)
	v_pk_fma_f32 v[40:41], v[168:169], v[230:231], v[40:41] op_sel_hi:[1,0,1]
	v_pk_fma_f32 v[38:39], v[166:167], v[230:231], v[38:39] op_sel_hi:[1,0,1]
	v_pk_fma_f32 v[36:37], v[168:169], v[230:231], v[36:37] op_sel:[0,1,0]
	v_pk_fma_f32 v[34:35], v[166:167], v[230:231], v[34:35] op_sel:[0,1,0]
	v_pk_fma_f32 v[28:29], v[168:169], v[232:233], v[28:29] op_sel_hi:[1,0,1]
	v_pk_fma_f32 v[26:27], v[166:167], v[232:233], v[26:27] op_sel_hi:[1,0,1]
	v_pk_fma_f32 v[24:25], v[168:169], v[232:233], v[24:25] op_sel:[0,1,0]
	v_pk_fma_f32 v[22:23], v[166:167], v[232:233], v[22:23] op_sel:[0,1,0]
	ds_read_b128 v[202:205], v43 offset:384
	ds_read_b128 v[206:209], v43 offset:400
	ds_read_b128 v[210:213], v43 offset:416
	ds_read_b128 v[214:217], v43 offset:432
	ds_read_b128 v[218:221], v43 offset:448
	ds_read_b128 v[222:225], v43 offset:464
	ds_read_b128 v[226:229], v43 offset:480
	ds_read_b128 v[230:233], v43 offset:496
	s_waitcnt vmcnt(7) lgkmcnt(7)
	v_pk_fma_f32 v[40:41], v[172:173], v[202:203], v[40:41] op_sel_hi:[1,0,1]
	v_pk_fma_f32 v[38:39], v[170:171], v[202:203], v[38:39] op_sel_hi:[1,0,1]
	v_pk_fma_f32 v[36:37], v[172:173], v[202:203], v[36:37] op_sel:[0,1,0]
	v_pk_fma_f32 v[34:35], v[170:171], v[202:203], v[34:35] op_sel:[0,1,0]
	v_pk_fma_f32 v[28:29], v[172:173], v[204:205], v[28:29] op_sel_hi:[1,0,1]
	v_pk_fma_f32 v[26:27], v[170:171], v[204:205], v[26:27] op_sel_hi:[1,0,1]
	v_pk_fma_f32 v[24:25], v[172:173], v[204:205], v[24:25] op_sel:[0,1,0]
	v_pk_fma_f32 v[22:23], v[170:171], v[204:205], v[22:23] op_sel:[0,1,0]
	s_waitcnt vmcnt(6) lgkmcnt(6)
	v_pk_fma_f32 v[40:41], v[176:177], v[206:207], v[40:41] op_sel_hi:[1,0,1]
	v_pk_fma_f32 v[38:39], v[174:175], v[206:207], v[38:39] op_sel_hi:[1,0,1]
	v_pk_fma_f32 v[36:37], v[176:177], v[206:207], v[36:37] op_sel:[0,1,0]
	v_pk_fma_f32 v[34:35], v[174:175], v[206:207], v[34:35] op_sel:[0,1,0]
	v_pk_fma_f32 v[28:29], v[176:177], v[208:209], v[28:29] op_sel_hi:[1,0,1]
	v_pk_fma_f32 v[26:27], v[174:175], v[208:209], v[26:27] op_sel_hi:[1,0,1]
	v_pk_fma_f32 v[24:25], v[176:177], v[208:209], v[24:25] op_sel:[0,1,0]
	v_pk_fma_f32 v[22:23], v[174:175], v[208:209], v[22:23] op_sel:[0,1,0]
	s_waitcnt vmcnt(5) lgkmcnt(5)
	v_pk_fma_f32 v[40:41], v[180:181], v[210:211], v[40:41] op_sel_hi:[1,0,1]
	v_pk_fma_f32 v[38:39], v[178:179], v[210:211], v[38:39] op_sel_hi:[1,0,1]
	v_pk_fma_f32 v[36:37], v[180:181], v[210:211], v[36:37] op_sel:[0,1,0]
	v_pk_fma_f32 v[34:35], v[178:179], v[210:211], v[34:35] op_sel:[0,1,0]
	v_pk_fma_f32 v[28:29], v[180:181], v[212:213], v[28:29] op_sel_hi:[1,0,1]
	v_pk_fma_f32 v[26:27], v[178:179], v[212:213], v[26:27] op_sel_hi:[1,0,1]
	v_pk_fma_f32 v[24:25], v[180:181], v[212:213], v[24:25] op_sel:[0,1,0]
	v_pk_fma_f32 v[22:23], v[178:179], v[212:213], v[22:23] op_sel:[0,1,0]
	s_waitcnt vmcnt(4) lgkmcnt(4)
	v_pk_fma_f32 v[40:41], v[184:185], v[214:215], v[40:41] op_sel_hi:[1,0,1]
	v_pk_fma_f32 v[38:39], v[182:183], v[214:215], v[38:39] op_sel_hi:[1,0,1]
	v_pk_fma_f32 v[36:37], v[184:185], v[214:215], v[36:37] op_sel:[0,1,0]
	v_pk_fma_f32 v[34:35], v[182:183], v[214:215], v[34:35] op_sel:[0,1,0]
	v_pk_fma_f32 v[28:29], v[184:185], v[216:217], v[28:29] op_sel_hi:[1,0,1]
	v_pk_fma_f32 v[26:27], v[182:183], v[216:217], v[26:27] op_sel_hi:[1,0,1]
	v_pk_fma_f32 v[24:25], v[184:185], v[216:217], v[24:25] op_sel:[0,1,0]
	v_pk_fma_f32 v[22:23], v[182:183], v[216:217], v[22:23] op_sel:[0,1,0]
	s_waitcnt vmcnt(3) lgkmcnt(3)
	v_pk_fma_f32 v[40:41], v[188:189], v[218:219], v[40:41] op_sel_hi:[1,0,1]
	v_pk_fma_f32 v[38:39], v[186:187], v[218:219], v[38:39] op_sel_hi:[1,0,1]
	v_pk_fma_f32 v[36:37], v[188:189], v[218:219], v[36:37] op_sel:[0,1,0]
	v_pk_fma_f32 v[34:35], v[186:187], v[218:219], v[34:35] op_sel:[0,1,0]
	v_pk_fma_f32 v[28:29], v[188:189], v[220:221], v[28:29] op_sel_hi:[1,0,1]
	v_pk_fma_f32 v[26:27], v[186:187], v[220:221], v[26:27] op_sel_hi:[1,0,1]
	v_pk_fma_f32 v[24:25], v[188:189], v[220:221], v[24:25] op_sel:[0,1,0]
	v_pk_fma_f32 v[22:23], v[186:187], v[220:221], v[22:23] op_sel:[0,1,0]
	s_waitcnt vmcnt(2) lgkmcnt(2)
	v_pk_fma_f32 v[40:41], v[192:193], v[222:223], v[40:41] op_sel_hi:[1,0,1]
	v_pk_fma_f32 v[38:39], v[190:191], v[222:223], v[38:39] op_sel_hi:[1,0,1]
	v_pk_fma_f32 v[36:37], v[192:193], v[222:223], v[36:37] op_sel:[0,1,0]
	v_pk_fma_f32 v[34:35], v[190:191], v[222:223], v[34:35] op_sel:[0,1,0]
	v_pk_fma_f32 v[28:29], v[192:193], v[224:225], v[28:29] op_sel_hi:[1,0,1]
	v_pk_fma_f32 v[26:27], v[190:191], v[224:225], v[26:27] op_sel_hi:[1,0,1]
	v_pk_fma_f32 v[24:25], v[192:193], v[224:225], v[24:25] op_sel:[0,1,0]
	v_pk_fma_f32 v[22:23], v[190:191], v[224:225], v[22:23] op_sel:[0,1,0]
	s_waitcnt vmcnt(1) lgkmcnt(1)
	v_pk_fma_f32 v[40:41], v[196:197], v[226:227], v[40:41] op_sel_hi:[1,0,1]
	v_pk_fma_f32 v[38:39], v[194:195], v[226:227], v[38:39] op_sel_hi:[1,0,1]
	v_pk_fma_f32 v[36:37], v[196:197], v[226:227], v[36:37] op_sel:[0,1,0]
	v_pk_fma_f32 v[34:35], v[194:195], v[226:227], v[34:35] op_sel:[0,1,0]
	v_pk_fma_f32 v[28:29], v[196:197], v[228:229], v[28:29] op_sel_hi:[1,0,1]
	v_pk_fma_f32 v[26:27], v[194:195], v[228:229], v[26:27] op_sel_hi:[1,0,1]
	v_pk_fma_f32 v[24:25], v[196:197], v[228:229], v[24:25] op_sel:[0,1,0]
	v_pk_fma_f32 v[22:23], v[194:195], v[228:229], v[22:23] op_sel:[0,1,0]
	s_waitcnt vmcnt(0) lgkmcnt(0)
	v_pk_fma_f32 v[40:41], v[200:201], v[230:231], v[40:41] op_sel_hi:[1,0,1]
	v_pk_fma_f32 v[38:39], v[198:199], v[230:231], v[38:39] op_sel_hi:[1,0,1]
	v_pk_fma_f32 v[36:37], v[200:201], v[230:231], v[36:37] op_sel:[0,1,0]
	v_pk_fma_f32 v[34:35], v[198:199], v[230:231], v[34:35] op_sel:[0,1,0]
	v_pk_fma_f32 v[28:29], v[200:201], v[232:233], v[28:29] op_sel_hi:[1,0,1]
	v_pk_fma_f32 v[26:27], v[198:199], v[232:233], v[26:27] op_sel_hi:[1,0,1]
	v_pk_fma_f32 v[24:25], v[200:201], v[232:233], v[24:25] op_sel:[0,1,0]
	v_pk_fma_f32 v[22:23], v[198:199], v[232:233], v[22:23] op_sel:[0,1,0]
	s_addk_i32 s19, 0x200
	s_cmpk_eq_i32 s19, 0x800
	s_cbranch_scc0 .LBB0_729
	s_movk_i32 s0, 0x400
	v_lshl_add_u32 v0, v42, 6, 0
	v_cmp_gt_i32_e32 vcc, s0, v42
	ds_write_b128 v0, v[38:41] offset:16384
	ds_write_b128 v0, v[34:37] offset:16400
	ds_write_b128 v0, v[26:29] offset:16416
	ds_write_b128 v0, v[22:25] offset:16432
	s_waitcnt lgkmcnt(0)
	s_barrier
	s_and_saveexec_b64 s[0:1], vcc
	s_cbranch_execz .LBB0_716
	v_and_b32_e32 v2, 3, v46
	v_lshlrev_b32_e32 v3, 4, v42
	s_lshl_b64 s[26:27], s[22:23], 2
	v_and_b32_e32 v3, 0xfc0, v3
	v_lshlrev_b32_e32 v2, 2, v2
	s_add_u32 s24, s24, s26
	v_mov_b32_e32 v0, 2
	v_add3_u32 v6, 0, v3, v2
	v_add_u32_sdwa v2, s22, v42 dst_sel:DWORD dst_unused:UNUSED_PAD src0_sel:DWORD src1_sel:BYTE_0
	s_addc_u32 s25, s25, s27
	v_lshlrev_b32_sdwa v0, v0, v42 dst_sel:DWORD dst_unused:UNUSED_PAD src0_sel:DWORD src1_sel:BYTE_0
	v_ashrrev_i32_e32 v3, 31, v2
	v_lshl_add_u64 v[2:3], v[2:3], 2, s[20:21]
	v_lshl_add_u64 v[4:5], s[24:25], 0, v[0:1]
	s_mov_b64 s[20:21], 0
